# GEMM phases: one static s_setprio 1 for waves 4-7 (no per-phase toggles)
# baseline (speedup 1.0000x reference)
.LBB0_290:
	s_or_b64 exec, exec, s[2:3]
	s_cmp_eq_u32 s50, 0
	s_mov_b64 s[2:3], s[66:67]
	s_mov_b32 s26, s70
	s_mov_b32 s27, s68
	v_mov_b32_e32 v10, v178
	s_cselect_b64 s[10:11], -1, 0
	s_waitcnt lgkmcnt(0)
	s_barrier
	v_readfirstlane_b32 s100, v178
	s_bitcmp1_b32 s100, 8
	s_cbranch_scc0 .Lprio_skip_1
	s_setprio 1
.Lprio_skip_1:
	s_cmpk_gt_i32 s27, 0xaff
	v_readfirstlane_b32 s28, v10
	s_cbranch_scc1 .LBB0_302
	v_lshlrev_b32_e32 v1, 4, v10
	v_add_u32_e32 v2, 0x2000, v1
	v_ashrrev_i32_e32 v3, 31, v2
	v_lshrrev_b32_e32 v3, 22, v3
	v_add_u32_e32 v3, v2, v3
	v_ashrrev_i32_e32 v11, 10, v3
	s_load_dwordx2 s[2:3], s[2:3], 0x120
	v_mul_i32_i24_e32 v3, 0x400, v11
	v_sub_u32_e32 v2, v2, v3
	v_lshrrev_b32_e32 v3, 4, v2
	v_bitop3_b32 v2, v3, v2, 32 bitop3:0x6c
	v_ashrrev_i32_e32 v3, 31, v2
	s_waitcnt lgkmcnt(0)
	s_add_u32 s29, s2, 0x15200000
	v_lshrrev_b32_e32 v3, 26, v3
	s_addc_u32 s30, s3, 0
	v_add_u32_e32 v3, v2, v3
	v_lshlrev_b32_e32 v4, 3, v11
	s_and_b64 s[4:5], s[10:11], exec
	v_ashrrev_i32_e32 v12, 6, v3
	v_and_b32_e32 v4, -16, v4
	s_cselect_b32 s4, 0, 0xb00000
	v_add_u32_e32 v4, v12, v4
	s_add_u32 s31, s2, s4
	v_and_b32_e32 v5, 3, v12
	s_mov_b32 s4, 0x1fffe0
	v_lshrrev_b32_e32 v6, 2, v4
	v_lshlrev_b32_e32 v7, 1, v4
	v_and_b32_e32 v3, 0xc0, v3
	v_and_or_b32 v5, v4, s4, v5
	v_and_b32_e32 v6, 4, v6
	v_and_b32_e32 v7, 24, v7
	v_sub_u32_e32 v2, v2, v3
	v_or3_b32 v5, v5, v6, v7
	v_lshlrev_b32_e32 v6, 5, v11
	v_ashrrev_i16_sdwa v2, v254, sext(v2) dst_sel:DWORD dst_unused:UNUSED_PAD src0_sel:DWORD src1_sel:BYTE_0
	v_and_b32_e32 v6, 32, v6
	v_bfe_i32 v13, v2, 0, 16
	v_add_lshl_u32 v2, v6, v13, 1
	v_lshl_add_u32 v130, v5, 11, v2
	v_lshl_add_u32 v132, v4, 11, v2
	v_bfe_i32 v2, v10, 27, 1
	v_lshrrev_b32_e32 v2, 22, v2
	v_add_u32_e32 v2, v1, v2
	v_and_b32_e32 v2, 0xfffffc00, v2
	v_sub_u32_e32 v1, v1, v2
	v_lshrrev_b32_e32 v2, 4, v1
	v_bitop3_b32 v2, v2, v1, 32 bitop3:0x6c
	v_ashrrev_i32_e32 v1, 31, v1
	v_lshrrev_b32_e32 v1, 26, v1
	v_add_u32_e32 v1, v2, v1
	v_ashrrev_i32_e32 v14, 6, v1
	v_ashrrev_i32_e32 v1, 31, v10
	v_lshrrev_b32_e32 v1, 26, v1
	v_add_u32_e32 v1, v10, v1
	v_ashrrev_i32_e32 v15, 6, v1
	v_lshlrev_b32_e32 v1, 3, v15
	v_and_b32_e32 v1, -16, v1
	s_addc_u32 s33, s3, 0
	s_ashr_i32 s34, s27, 31
	v_add_u32_e32 v1, v14, v1
	v_and_b32_e32 v3, 3, v14
	v_and_or_b32 v3, v1, s4, v3
	s_lshr_b32 s4, s34, 29
	s_add_i32 s4, s27, s4
	s_ashr_i32 s6, s28, 6
	s_ashr_i32 s7, s4, 3
	s_and_b32 s4, s4, -8
	s_ashr_i32 s5, s28, 8
	s_lshl_b32 s35, s6, 10
	s_sub_i32 s4, s27, s4
	s_cmp_lt_i32 s4, 0
	s_movk_i32 s8, 0x161
	s_cselect_b32 s8, s8, 0x160
	s_mul_i32 s4, s8, s4
	s_add_i32 s4, s4, s7
	s_mul_hi_i32 s7, s4, 0x2e8ba2e9
	s_lshr_b32 s8, s7, 31
	s_ashr_i32 s7, s7, 5
	s_add_i32 s7, s7, s8
	s_lshl_b32 s8, s7, 3
	s_mulk_i32 s7, 0xb0
	s_sub_i32 s7, s4, s7
	s_bfe_u32 s4, s7, 0x3001c
	s_add_i32 s9, s7, s4
	s_sext_i32_i16 s4, s9
	s_and_b32 s9, s9, 0xfff8
	v_lshrrev_b32_e32 v4, 2, v1
	v_lshlrev_b32_e32 v5, 1, v1
	s_sub_i32 s7, s7, s9
	v_and_b32_e32 v4, 4, v4
	v_and_b32_e32 v5, 24, v5
	s_sext_i32_i16 s7, s7
	v_or3_b32 v3, v3, v4, v5
	v_mul_i32_i24_e32 v5, 64, v14
	s_lshr_b32 s4, s4, 3
	s_add_i32 s18, s8, s7
	v_sub_u32_e32 v2, v2, v5
	s_ashr_i32 s19, s18, 31
	s_bfe_i64 s[12:13], s[4:5], 0x100000
	v_lshlrev_b32_e32 v4, 5, v15
	v_ashrrev_i16_sdwa v2, v254, sext(v2) dst_sel:DWORD dst_unused:UNUSED_PAD src0_sel:DWORD src1_sel:BYTE_0
	s_lshl_b64 s[8:9], s[18:19], 19
	s_lshl_b64 s[12:13], s[12:13], 19
	v_and_b32_e32 v4, 32, v4
	v_bfe_i32 v16, v2, 0, 16
	s_add_u32 s22, s31, s12
	v_add_lshl_u32 v2, v4, v16, 1
	s_addc_u32 s23, s33, s13
	s_add_i32 s19, s35, 0
	v_lshl_add_u32 v134, v3, 11, v2
	s_add_i32 m0, s19, 0x10000
	v_lshl_add_u32 v136, v1, 11, v2
	global_load_lds_dwordx4 v134, s[22:23]
	s_add_i32 m0, s19, 0x12000
	s_add_u32 s20, s29, s8
	global_load_lds_dwordx4 v130, s[22:23]
	s_addc_u32 s21, s30, s9
	s_mov_b32 m0, s19
	s_add_i32 s36, s19, 0x2000
	global_load_lds_dwordx4 v136, s[20:21]
	s_mov_b32 m0, s36
	s_add_u32 s8, s22, 0x40000
	global_load_lds_dwordx4 v132, s[20:21]
	s_addc_u32 s9, s23, 0
	s_add_i32 m0, s19, 0x14000
	v_mov_b32_e32 v135, v0
	global_load_lds_dwordx4 v134, s[8:9]
	s_add_i32 m0, s19, 0x16000
	v_mov_b32_e32 v131, v0
	global_load_lds_dwordx4 v130, s[8:9]
	s_add_u32 s8, s20, 0x40000
	s_addc_u32 s9, s21, 0
	s_add_i32 s37, s19, 0x4000
	s_mov_b32 m0, s37
	s_add_i32 s38, s19, 0x6000
	global_load_lds_dwordx4 v136, s[8:9]
	s_mov_b32 m0, s38
	v_mov_b32_e32 v137, v0
	global_load_lds_dwordx4 v132, s[8:9]
	v_mov_b32_e32 v133, v0
	v_lshl_add_u64 v[8:9], s[22:23], 0, v[134:135]
	v_lshl_add_u64 v[6:7], s[22:23], 0, v[130:131]
	v_lshl_add_u64 v[4:5], s[20:21], 0, v[136:137]
	s_cmp_lg_u32 s5, 1
	v_lshl_add_u64 v[2:3], s[20:21], 0, v[132:133]
	s_cbranch_scc1 .LBB0_293
	s_barrier

.LBB0_302:
	s_setprio 0
	s_mov_b64 s[4:5], s[66:67]
	s_getreg_b32 s6, hwreg(HW_REG_XCC_ID, 0, 4)
	s_waitcnt vmcnt(0)
	s_waitcnt vmcnt(0) lgkmcnt(0)
	s_barrier
	s_mov_b64 s[2:3], exec
	v_readlane_b32 s8, v255, 0
	v_readlane_b32 s9, v255, 1
	s_and_b64 s[8:9], s[2:3], s[8:9]
	s_mov_b64 exec, s[8:9]
	s_cbranch_execz .LBB0_354
	v_readlane_b32 s7, v255, 3
	s_load_dwordx2 s[4:5], s[4:5], 0x120
	s_waitcnt vmcnt(0) expcnt(0) lgkmcnt(0)
	v_mov_b32_e32 v1, s7
	ds_read_b32 v3, v1
	v_readlane_b32 s7, v255, 4
	s_and_b32 s33, s6, 15
	s_waitcnt lgkmcnt(0)
	v_cmp_ne_u32_e32 vcc, 0, v3
	v_mov_b32_e32 v1, s7
	ds_read_b32 v2, v1
	s_cbranch_vccnz .LBB0_318
	s_add_u32 s6, s4, 0x31c0200
	s_addc_u32 s7, s5, 0
	s_add_u32 s8, s4, 0x31c0400
	s_addc_u32 s9, s5, 0
	s_add_u32 s12, s4, 0x31c0500
	s_addc_u32 s13, s5, 0
	s_add_u32 s14, s4, 0x31c0600
	s_addc_u32 s15, s5, 0
	s_add_u32 s18, s4, 0x31c0700
	s_addc_u32 s19, s5, 0
	s_add_u32 s20, s4, 0x31c0800
	s_addc_u32 s21, s5, 0
	s_add_u32 s22, s4, 0x31c0900
	s_addc_u32 s23, s5, 0
	s_add_u32 s24, s4, 0x31c0a00
	s_addc_u32 s25, s5, 0
	s_add_u32 s26, s4, 0x31c0b00
	s_addc_u32 s27, s5, 0
	s_add_u32 s28, s4, 0x31c0c00
	s_addc_u32 s29, s5, 0
	s_add_u32 s30, s4, 0x31c0d00
	s_addc_u32 s31, s5, 0
	s_add_u32 s34, s4, 0x31c0e00
	s_addc_u32 s35, s5, 0
	s_add_u32 s36, s4, 0x31c0f00
	s_addc_u32 s37, s5, 0
	s_add_u32 s38, s4, 0x31c1000
	s_addc_u32 s39, s5, 0
	s_add_u32 s40, s4, 0x31c1100
	s_addc_u32 s41, s5, 0
	s_add_u32 s42, s4, 0x31c1200
	s_addc_u32 s43, s5, 0
	s_add_u32 s44, s4, 0x31c1300
	s_addc_u32 s45, s5, 0
	s_mov_b32 s54, 1
	s_branch .LBB0_306

.LBB0_354:
	s_or_b64 exec, exec, s[2:3]
	s_mov_b64 s[2:3], s[66:67]
	s_waitcnt lgkmcnt(0)
	s_barrier
	s_load_dwordx4 s[12:15], s[2:3], 0x118
	v_readlane_b32 s4, v255, 29
	v_readlane_b32 s5, v255, 30
	s_waitcnt lgkmcnt(0)
	v_readfirstlane_b32 s100, v178
	s_bitcmp1_b32 s100, 8
	s_cbranch_scc0 .Lprio_skip_2
	s_setprio 1
.Lprio_skip_2:
	s_add_u32 s6, s14, s4
	s_addc_u32 s7, s15, s5
	s_add_u32 s22, s14, 0x3200000
	s_addc_u32 s23, s15, 0
	s_and_b64 s[4:5], s[10:11], exec
	s_mov_b32 s4, 0x1b80000
	s_cselect_b32 s4, 0x1600000, s4
	s_add_u32 s24, s14, s4
	s_addc_u32 s25, s15, 0
	s_add_u32 s4, s6, s53
	s_addc_u32 s5, s7, 0
	s_add_u32 s26, s4, 0x3002000
	s_addc_u32 s27, s5, 0
	s_and_b64 vcc, exec, s[16:17]
	s_cbranch_vccz .LBB0_380
	s_mov_b32 s28, s70
	s_mov_b32 s29, s68
	v_mov_b32_e32 v18, v178
	s_cmpk_gt_i32 s29, 0x1ff
	v_readfirstlane_b32 s30, v18
	s_cbranch_scc1 .LBB0_379
	s_ashr_i32 s31, s29, 31
	s_lshr_b32 s4, s31, 29
	s_add_i32 s7, s29, s4
	s_and_b32 s4, s7, -8
	s_sub_i32 s8, s29, s4
	s_cmp_gt_i32 s8, -1
	s_mov_b64 s[4:5], -1
	s_cbranch_scc0 .LBB0_358
	s_lshl_b32 s6, s8, 6
	s_mov_b64 s[4:5], 0

.LBB0_405:
	s_setprio 0
	s_mov_b64 s[4:5], s[66:67]
	s_getreg_b32 s6, hwreg(HW_REG_XCC_ID, 0, 4)
	s_waitcnt vmcnt(0)
	s_waitcnt lgkmcnt(0)
	s_barrier
	s_mov_b64 s[2:3], exec
	v_readlane_b32 s8, v255, 0
	v_readlane_b32 s9, v255, 1
	s_and_b64 s[8:9], s[2:3], s[8:9]
	s_mov_b64 exec, s[8:9]
	s_cbranch_execz .LBB0_457
	v_readlane_b32 s7, v255, 3
	s_load_dwordx2 s[4:5], s[4:5], 0x120
	s_waitcnt vmcnt(0) expcnt(0) lgkmcnt(0)
	v_mov_b32_e32 v1, s7
	ds_read_b32 v3, v1
	v_readlane_b32 s7, v255, 4
	s_and_b32 s33, s6, 15
	s_waitcnt lgkmcnt(0)
	v_cmp_ne_u32_e32 vcc, 0, v3
	v_mov_b32_e32 v1, s7
	ds_read_b32 v2, v1
	s_cbranch_vccnz .LBB0_421
	s_add_u32 s6, s4, 0x31c0200
	s_addc_u32 s7, s5, 0
	s_add_u32 s8, s4, 0x31c0400
	s_addc_u32 s9, s5, 0
	s_add_u32 s12, s4, 0x31c0500
	s_addc_u32 s13, s5, 0
	s_add_u32 s14, s4, 0x31c0600
	s_addc_u32 s15, s5, 0
	s_add_u32 s16, s4, 0x31c0700
	s_addc_u32 s17, s5, 0
	s_add_u32 s18, s4, 0x31c0800
	s_addc_u32 s19, s5, 0
	s_add_u32 s20, s4, 0x31c0900
	s_addc_u32 s21, s5, 0
	s_add_u32 s22, s4, 0x31c0a00
	s_addc_u32 s23, s5, 0
	s_add_u32 s24, s4, 0x31c0b00
	s_addc_u32 s25, s5, 0
	s_add_u32 s26, s4, 0x31c0c00
	s_addc_u32 s27, s5, 0
	s_add_u32 s28, s4, 0x31c0d00
	s_addc_u32 s29, s5, 0
	s_add_u32 s30, s4, 0x31c0e00
	s_addc_u32 s31, s5, 0
	s_add_u32 s34, s4, 0x31c0f00
	s_addc_u32 s35, s5, 0
	s_add_u32 s36, s4, 0x31c1000
	s_addc_u32 s37, s5, 0
	s_add_u32 s38, s4, 0x31c1100
	s_addc_u32 s39, s5, 0
	s_add_u32 s40, s4, 0x31c1200
	s_addc_u32 s41, s5, 0
	s_add_u32 s42, s4, 0x31c1300
	s_addc_u32 s43, s5, 0
	s_mov_b32 s50, 1
	s_branch .LBB0_409

.LBB0_519:
	s_or_b64 exec, exec, s[2:3]
	v_readlane_b32 s6, v255, 31
	s_cmp_gt_u32 s6, 1
	s_cselect_b64 s[2:3], -1, 0
	s_cmp_lt_u32 s6, 2
	s_cselect_b64 s[8:9], -1, 0
	s_and_b64 s[6:7], s[8:9], exec
	s_cselect_b32 s6, 19, 16
	s_movk_i32 s7, 0x1200
	s_mov_b64 s[4:5], s[66:67]
	s_cselect_b32 s7, s7, 0x1000
	s_mov_b32 s26, s70
	s_mov_b32 s27, s68
	v_mov_b32_e32 v16, v178
	s_lshl_b32 s80, s6, 7
	s_waitcnt lgkmcnt(0)
	s_barrier
	v_writelane_b32 v255, s7, 32
	v_readfirstlane_b32 s100, v178
	s_bitcmp1_b32 s100, 8
	s_cbranch_scc0 .Lprio_skip_3
	s_setprio 1
.Lprio_skip_3:
	s_cmp_ge_i32 s27, s80
	v_readfirstlane_b32 s28, v16
	s_cbranch_scc1 .LBB0_537
	v_lshlrev_b32_e32 v1, 4, v16
	v_add_u32_e32 v2, 0x2000, v1
	v_ashrrev_i32_e32 v3, 31, v2
	v_lshrrev_b32_e32 v3, 22, v3
	v_add_u32_e32 v3, v2, v3
	v_ashrrev_i32_e32 v10, 10, v3
	v_mul_i32_i24_e32 v3, 0x400, v10
	v_sub_u32_e32 v2, v2, v3
	v_lshrrev_b32_e32 v3, 4, v2
	v_bitop3_b32 v2, v3, v2, 32 bitop3:0x6c
	v_ashrrev_i32_e32 v3, 31, v2
	v_lshrrev_b32_e32 v3, 26, v3
	v_add_u32_e32 v3, v2, v3
	v_lshlrev_b32_e32 v4, 3, v10
	v_ashrrev_i32_e32 v11, 6, v3
	v_and_b32_e32 v4, -16, v4
	v_add_u32_e32 v4, v11, v4
	v_and_b32_e32 v5, 3, v11
	s_mov_b32 s7, 0x1fffe0
	v_lshrrev_b32_e32 v6, 2, v4
	v_lshlrev_b32_e32 v7, 1, v4
	v_and_b32_e32 v3, 0xc0, v3
	v_and_or_b32 v5, v4, s7, v5
	v_and_b32_e32 v6, 4, v6
	v_and_b32_e32 v7, 24, v7
	v_sub_u32_e32 v2, v2, v3
	v_or3_b32 v5, v5, v6, v7
	v_lshlrev_b32_e32 v6, 5, v10
	v_ashrrev_i16_sdwa v2, v254, sext(v2) dst_sel:DWORD dst_unused:UNUSED_PAD src0_sel:DWORD src1_sel:BYTE_0
	v_and_b32_e32 v6, 32, v6
	v_bfe_i32 v12, v2, 0, 16
	v_add_lshl_u32 v2, v6, v12, 1
	v_lshl_add_u32 v130, v5, 11, v2
	v_lshl_add_u32 v132, v4, 11, v2
	v_bfe_i32 v2, v16, 27, 1
	v_lshrrev_b32_e32 v2, 22, v2
	v_add_u32_e32 v2, v1, v2
	v_and_b32_e32 v2, 0xfffffc00, v2
	v_sub_u32_e32 v1, v1, v2
	v_lshrrev_b32_e32 v2, 4, v1
	v_bitop3_b32 v2, v2, v1, 32 bitop3:0x6c
	v_ashrrev_i32_e32 v1, 31, v1
	v_lshrrev_b32_e32 v1, 26, v1
	v_add_u32_e32 v1, v2, v1
	v_ashrrev_i32_e32 v13, 6, v1
	v_ashrrev_i32_e32 v1, 31, v16
	v_lshrrev_b32_e32 v1, 26, v1
	v_add_u32_e32 v1, v16, v1
	v_ashrrev_i32_e32 v14, 6, v1
	s_load_dwordx2 s[4:5], s[4:5], 0x120
	v_lshlrev_b32_e32 v1, 3, v14
	v_and_b32_e32 v1, -16, v1
	v_add_u32_e32 v1, v13, v1
	v_and_b32_e32 v3, 3, v13
	v_lshrrev_b32_e32 v4, 2, v1
	v_lshlrev_b32_e32 v5, 1, v1
	v_and_or_b32 v3, v1, s7, v3
	v_and_b32_e32 v4, 4, v4
	v_and_b32_e32 v5, 24, v5
	s_waitcnt lgkmcnt(0)
	s_add_u32 s29, s4, 0x15200000
	v_or3_b32 v3, v3, v4, v5
	v_mul_i32_i24_e32 v5, 64, v13
	s_addc_u32 s30, s5, 0
	v_sub_u32_e32 v2, v2, v5
	s_add_u32 s31, s4, 0x2100000
	v_lshlrev_b32_e32 v4, 5, v14
	v_ashrrev_i16_sdwa v2, v254, sext(v2) dst_sel:DWORD dst_unused:UNUSED_PAD src0_sel:DWORD src1_sel:BYTE_0
	s_addc_u32 s33, s5, 0
	v_and_b32_e32 v4, 32, v4
	v_bfe_i32 v15, v2, 0, 16
	s_lshl_b32 s37, s6, 3
	v_add_lshl_u32 v2, v4, v15, 1
	s_abs_i32 s38, s37
	v_lshl_add_u32 v136, v1, 11, v2
	v_cvt_f32_u32_e32 v1, s38
	s_ashr_i32 s34, s27, 31
	s_lshr_b32 s7, s34, 29
	s_add_i32 s7, s27, s7
	v_rcp_iflag_f32_e32 v1, v1
	s_ashr_i32 s10, s7, 3
	s_and_b32 s7, s7, -8
	s_sub_i32 s7, s27, s7
	v_mul_f32_e32 v1, 0x4f7ffffe, v1
	v_cvt_u32_f32_e32 v1, v1
	s_lshl_b32 s36, s6, 4
	s_lshr_b32 s11, s7, 31
	s_or_b32 s11, s11, s36
	s_mul_i32 s7, s11, s7
	s_sub_i32 s11, 0, s38
	v_readfirstlane_b32 s40, v1
	s_add_i32 s7, s7, s10
	s_mul_i32 s11, s11, s40
	s_ashr_i32 s10, s7, 31
	s_bfe_i32 s39, s6, 0x1001c
	s_mul_hi_u32 s11, s40, s11
	s_xor_b32 s6, s10, s39
	s_abs_i32 s10, s7
	s_add_i32 s40, s40, s11
	s_mul_hi_u32 s11, s10, s40
	s_mul_i32 s14, s11, s38
	s_ashr_i32 s13, s28, 6
	s_sub_i32 s10, s10, s14
	s_ashr_i32 s12, s28, 8
	s_lshl_b32 s35, s13, 10
	s_add_i32 s14, s11, 1
	s_sub_i32 s15, s10, s38
	s_cmp_ge_u32 s10, s38
	s_cselect_b32 s11, s14, s11
	s_cselect_b32 s10, s15, s10
	s_add_i32 s14, s11, 1
	s_cmp_ge_u32 s10, s38
	s_cselect_b32 s10, s14, s11
	s_xor_b32 s10, s10, s6
	s_sub_i32 s6, s10, s6
	s_lshl_b32 s10, s6, 3
	s_sub_i32 s11, 0x80, s10
	s_min_i32 s11, s11, 8
	v_cvt_f32_i32_e32 v1, s11
	s_mul_i32 s6, s6, s37
	s_sub_i32 s14, s7, s6
	v_lshl_add_u32 v134, v3, 11, v2
	v_cvt_f32_i32_e32 v2, s14
	v_rcp_iflag_f32_e32 v3, v1
	s_xor_b32 s6, s14, s11
	s_ashr_i32 s6, s6, 30
	s_or_b32 s15, s6, 1
	v_mul_f32_e32 v3, v2, v3
	v_trunc_f32_e32 v3, v3
	v_fma_f32 v2, -v3, v1, v2
	v_cvt_i32_f32_e32 v3, v3
	v_cmp_ge_f32_e64 s[6:7], |v2|, |v1|
	s_and_b64 s[6:7], s[6:7], exec
	s_cselect_b32 s6, s15, 0
	v_readfirstlane_b32 s7, v3
	s_add_i32 s6, s7, s6
	s_mul_i32 s7, s6, s11
	s_sub_i32 s7, s14, s7
	s_sext_i32_i16 s7, s7
	s_add_i32 s10, s10, s7
	s_ashr_i32 s11, s10, 31
	s_bfe_i64 s[16:17], s[6:7], 0x100000
	s_lshl_b64 s[14:15], s[10:11], 19
	s_lshl_b64 s[16:17], s[16:17], 19
	s_add_u32 s22, s31, s16
	s_addc_u32 s23, s33, s17
	s_add_i32 s41, s35, 0
	s_add_i32 m0, s41, 0x10000
	v_mov_b32_e32 v135, v0
	global_load_lds_dwordx4 v134, s[22:23]
	s_add_i32 m0, s41, 0x12000
	s_add_u32 s20, s29, s14
	global_load_lds_dwordx4 v130, s[22:23]
	s_addc_u32 s21, s30, s15
	s_mov_b32 m0, s41
	s_add_i32 s42, s41, 0x2000
	global_load_lds_dwordx4 v136, s[20:21]
	s_mov_b32 m0, s42
	s_add_u32 s14, s22, 0x40000
	global_load_lds_dwordx4 v132, s[20:21]
	s_addc_u32 s15, s23, 0
	s_add_i32 m0, s41, 0x14000
	v_mov_b32_e32 v131, v0
	global_load_lds_dwordx4 v134, s[14:15]
	s_add_i32 m0, s41, 0x16000
	v_mov_b32_e32 v137, v0
	global_load_lds_dwordx4 v130, s[14:15]
	s_add_u32 s14, s20, 0x40000
	s_addc_u32 s15, s21, 0
	s_add_i32 s43, s41, 0x4000
	s_mov_b32 m0, s43
	s_add_i32 s44, s41, 0x6000
	global_load_lds_dwordx4 v136, s[14:15]
	s_mov_b32 m0, s44
	v_mov_b32_e32 v133, v0
	global_load_lds_dwordx4 v132, s[14:15]
	v_lshl_add_u64 v[8:9], s[22:23], 0, v[134:135]
	v_lshl_add_u64 v[6:7], s[22:23], 0, v[130:131]
	v_lshl_add_u64 v[4:5], s[20:21], 0, v[136:137]
	s_cmp_lg_u32 s12, 1
	v_lshl_add_u64 v[2:3], s[20:21], 0, v[132:133]
	s_cbranch_scc1 .LBB0_522
	s_barrier

.LBB0_537:
	s_setprio 0
	s_mov_b64 s[6:7], s[66:67]
	s_getreg_b32 s8, hwreg(HW_REG_XCC_ID, 0, 4)
	s_waitcnt vmcnt(0)
	s_waitcnt vmcnt(0) lgkmcnt(0)
	s_barrier
	s_mov_b64 s[4:5], exec
	v_readlane_b32 s10, v255, 0
	v_readlane_b32 s11, v255, 1
	s_and_b64 s[10:11], s[4:5], s[10:11]
	s_mov_b64 exec, s[10:11]
	s_cbranch_execz .LBB0_589
	v_readlane_b32 s9, v255, 3
	s_load_dwordx2 s[6:7], s[6:7], 0x120
	s_waitcnt vmcnt(0) expcnt(0) lgkmcnt(0)
	v_mov_b32_e32 v1, s9
	ds_read_b32 v3, v1
	v_readlane_b32 s9, v255, 4
	s_and_b32 s33, s8, 15
	s_waitcnt lgkmcnt(0)
	v_cmp_ne_u32_e32 vcc, 0, v3
	v_mov_b32_e32 v1, s9
	ds_read_b32 v2, v1
	s_cbranch_vccnz .LBB0_553
	s_add_u32 s8, s6, 0x31c0200
	s_addc_u32 s9, s7, 0
	s_add_u32 s10, s6, 0x31c0400
	s_addc_u32 s11, s7, 0
	s_add_u32 s12, s6, 0x31c0500
	s_addc_u32 s13, s7, 0
	s_add_u32 s14, s6, 0x31c0600
	s_addc_u32 s15, s7, 0
	s_add_u32 s16, s6, 0x31c0700
	s_addc_u32 s17, s7, 0
	s_add_u32 s18, s6, 0x31c0800
	s_addc_u32 s19, s7, 0
	s_add_u32 s20, s6, 0x31c0900
	s_addc_u32 s21, s7, 0
	s_add_u32 s22, s6, 0x31c0a00
	s_addc_u32 s23, s7, 0
	s_add_u32 s24, s6, 0x31c0b00
	s_addc_u32 s25, s7, 0
	s_add_u32 s26, s6, 0x31c0c00
	s_addc_u32 s27, s7, 0
	s_add_u32 s28, s6, 0x31c0d00
	s_addc_u32 s29, s7, 0
	s_add_u32 s30, s6, 0x31c0e00
	s_addc_u32 s31, s7, 0
	s_add_u32 s34, s6, 0x31c0f00
	s_addc_u32 s35, s7, 0
	s_add_u32 s36, s6, 0x31c1000
	s_addc_u32 s37, s7, 0
	s_add_u32 s38, s6, 0x31c1100
	s_addc_u32 s39, s7, 0
	s_add_u32 s40, s6, 0x31c1200
	s_addc_u32 s41, s7, 0
	s_add_u32 s42, s6, 0x31c1300
	s_addc_u32 s43, s7, 0
	s_mov_b32 s50, 1
	s_branch .LBB0_541

.LBB0_1197:
	s_or_b64 exec, exec, s[2:3]
	s_mov_b64 s[4:5], s[66:67]
	s_mov_b32 s34, s70
	s_mov_b32 s12, s68
	v_mov_b32_e32 v1, v178
	s_waitcnt lgkmcnt(0)
	s_barrier
	v_readfirstlane_b32 s100, v178
	s_bitcmp1_b32 s100, 8
	s_cbranch_scc0 .Lprio_skip_4
	s_setprio 1
.Lprio_skip_4:
	s_cmpk_gt_i32 s12, 0x3ff
	v_readfirstlane_b32 s35, v1
	s_cbranch_scc1 .LBB0_1217
	s_ashr_i32 s13, s12, 31
	s_lshr_b32 s2, s13, 29
	s_add_i32 s10, s12, s2
	s_and_b32 s2, s10, -8
	s_sub_i32 s9, s12, s2
	s_cmp_gt_i32 s9, -1
	s_mov_b64 s[2:3], -1
	s_cbranch_scc0 .LBB0_1200
	s_lshl_b32 s8, s9, 7
	s_mov_b64 s[2:3], 0

.LBB0_1217:
	s_setprio 0
	s_mov_b64 s[4:5], s[66:67]
	s_getreg_b32 s6, hwreg(HW_REG_XCC_ID, 0, 4)
	s_waitcnt vmcnt(0)
	s_waitcnt lgkmcnt(0)
	s_barrier
	s_mov_b64 s[2:3], exec
	v_readlane_b32 s8, v255, 0
	v_readlane_b32 s9, v255, 1
	s_and_b64 s[8:9], s[2:3], s[8:9]
	s_movk_i32 s31, 0x6000
	s_movk_i32 s34, 0x4000
	s_mov_b32 s35, 0x10000
	s_mov_b64 exec, s[8:9]
	s_cbranch_execz .LBB0_1269
	v_readlane_b32 s7, v255, 3
	s_load_dwordx2 s[4:5], s[4:5], 0x120
	s_waitcnt vmcnt(0) expcnt(0) lgkmcnt(0)
	v_mov_b32_e32 v1, s7
	ds_read_b32 v3, v1
	v_readlane_b32 s7, v255, 4
	s_and_b32 s33, s6, 15
	s_waitcnt lgkmcnt(0)
	v_cmp_ne_u32_e32 vcc, 0, v3
	v_mov_b32_e32 v1, s7
	ds_read_b32 v2, v1
	s_cbranch_vccnz .LBB0_1233
	s_add_u32 s6, s4, 0x31c0200
	s_addc_u32 s7, s5, 0
	s_add_u32 s8, s4, 0x31c0400
	s_addc_u32 s9, s5, 0
	s_add_u32 s10, s4, 0x31c0500
	s_addc_u32 s11, s5, 0
	s_add_u32 s12, s4, 0x31c0600
	s_addc_u32 s13, s5, 0
	s_add_u32 s14, s4, 0x31c0700
	s_addc_u32 s15, s5, 0
	s_add_u32 s16, s4, 0x31c0800
	s_addc_u32 s17, s5, 0
	s_add_u32 s18, s4, 0x31c0900
	s_addc_u32 s19, s5, 0
	s_add_u32 s20, s4, 0x31c0a00
	s_addc_u32 s21, s5, 0
	s_add_u32 s22, s4, 0x31c0b00
	s_addc_u32 s23, s5, 0
	s_add_u32 s24, s4, 0x31c0c00
	s_addc_u32 s25, s5, 0
	s_add_u32 s26, s4, 0x31c0d00
	s_addc_u32 s27, s5, 0
	s_add_u32 s28, s4, 0x31c0e00
	s_addc_u32 s29, s5, 0
	s_add_u32 s30, s4, 0x31c0f00
	s_addc_u32 s31, s5, 0
	s_add_u32 s34, s4, 0x31c1000
	s_addc_u32 s35, s5, 0
	s_add_u32 s36, s4, 0x31c1100
	s_addc_u32 s37, s5, 0
	s_add_u32 s38, s4, 0x31c1200
	s_addc_u32 s39, s5, 0
	s_add_u32 s40, s4, 0x31c1300
	s_addc_u32 s41, s5, 0
	s_mov_b32 s48, 1
	s_branch .LBB0_1221

.LBB0_1391:
	s_mov_b64 s[6:7], s[66:67]
	s_mov_b32 s20, s70
	s_mov_b32 s21, s68
	s_waitcnt vmcnt(4)
	v_mov_b32_e32 v14, v178
	v_readfirstlane_b32 s100, v178
	s_bitcmp1_b32 s100, 8
	s_cbranch_scc0 .Lprio_skip_5
	s_setprio 1
.Lprio_skip_5:
	s_cmpk_gt_i32 s21, 0x1ff
	v_readfirstlane_b32 s22, v14
	s_cbranch_scc1 .LBB0_1413
	s_ashr_i32 s23, s21, 31
	s_lshr_b32 s8, s23, 29
	s_add_i32 s16, s21, s8
	s_and_b32 s8, s16, -8
	s_sub_i32 s15, s21, s8
	s_cmp_gt_i32 s15, -1
	s_mov_b64 s[12:13], -1
	s_cbranch_scc0 .LBB0_1394
	s_lshl_b32 s14, s15, 6
	s_mov_b64 s[12:13], 0

.LBB0_1413:
	s_setprio 0
	s_mov_b64 s[4:5], s[66:67]
	s_getreg_b32 s6, hwreg(HW_REG_XCC_ID, 0, 4)
	s_waitcnt vmcnt(0)
	s_waitcnt lgkmcnt(0)
	s_barrier
	s_mov_b64 s[2:3], exec
	v_readlane_b32 s8, v255, 0
	v_readlane_b32 s9, v255, 1
	s_and_b64 s[8:9], s[2:3], s[8:9]
	s_mov_b64 exec, s[8:9]
	s_cbranch_execnz .LBB0_1414
	s_getpc_b64 s[98:99]

	.amdhsa_kernel _Z14fwd_megakernel6Params
		.amdhsa_group_segment_fixed_size 0
		.amdhsa_private_segment_fixed_size 0
		.amdhsa_kernarg_size 552
		.amdhsa_user_sgpr_count 2
		.amdhsa_user_sgpr_dispatch_ptr 0
		.amdhsa_user_sgpr_queue_ptr 0
		.amdhsa_user_sgpr_kernarg_segment_ptr 1
		.amdhsa_user_sgpr_dispatch_id 0
		.amdhsa_user_sgpr_kernarg_preload_length 0
		.amdhsa_user_sgpr_kernarg_preload_offset 0
		.amdhsa_user_sgpr_private_segment_size 0
		.amdhsa_uses_dynamic_stack 0
		.amdhsa_enable_private_segment 0
		.amdhsa_system_sgpr_workgroup_id_x 1
		.amdhsa_system_sgpr_workgroup_id_y 0
		.amdhsa_system_sgpr_workgroup_id_z 0
		.amdhsa_system_sgpr_workgroup_info 0
		.amdhsa_system_vgpr_workitem_id 2
		.amdhsa_next_free_vgpr 256
		.amdhsa_next_free_sgpr 102
		.amdhsa_accum_offset 256
		.amdhsa_reserve_vcc 1
		.amdhsa_float_round_mode_32 0
		.amdhsa_float_round_mode_16_64 0
		.amdhsa_float_denorm_mode_32 3
		.amdhsa_float_denorm_mode_16_64 3
		.amdhsa_dx10_clamp 1
		.amdhsa_ieee_mode 1
		.amdhsa_fp16_overflow 0
		.amdhsa_tg_split 0
		.amdhsa_exception_fp_ieee_invalid_op 0
		.amdhsa_exception_fp_denorm_src 0
		.amdhsa_exception_fp_ieee_div_zero 0
		.amdhsa_exception_fp_ieee_overflow 0
		.amdhsa_exception_fp_ieee_underflow 0
		.amdhsa_exception_fp_ieee_inexact 0
		.amdhsa_exception_int_div_zero 0
	.end_amdhsa_kernel

amdhsa.kernels:
  - .agpr_count:     0
    .args:
      - .offset:         0
        .size:           296
        .value_kind:     by_value
      - .offset:         296
        .size:           4
        .value_kind:     hidden_block_count_x
      - .offset:         300
        .size:           4
        .value_kind:     hidden_block_count_y
      - .offset:         304
        .size:           4
        .value_kind:     hidden_block_count_z
      - .offset:         308
        .size:           2
        .value_kind:     hidden_group_size_x
      - .offset:         310
        .size:           2
        .value_kind:     hidden_group_size_y
      - .offset:         312
        .size:           2
        .value_kind:     hidden_group_size_z
      - .offset:         314
        .size:           2
        .value_kind:     hidden_remainder_x
      - .offset:         316
        .size:           2
        .value_kind:     hidden_remainder_y
      - .offset:         318
        .size:           2
        .value_kind:     hidden_remainder_z
      - .offset:         336
        .size:           8
        .value_kind:     hidden_global_offset_x
      - .offset:         344
        .size:           8
        .value_kind:     hidden_global_offset_y
      - .offset:         352
        .size:           8
        .value_kind:     hidden_global_offset_z
      - .offset:         360
        .size:           2
        .value_kind:     hidden_grid_dims
      - .offset:         384
        .size:           8
        .value_kind:     hidden_multigrid_sync_arg
      - .offset:         416
        .size:           4
        .value_kind:     hidden_dynamic_lds_size
    .group_segment_fixed_size: 0
    .kernarg_segment_align: 8
    .kernarg_segment_size: 552
    .language:       OpenCL C
    .language_version:
      - 2
      - 0
    .max_flat_workgroup_size: 512
    .name:           _Z14fwd_megakernel6Params
    .private_segment_fixed_size: 0
    .sgpr_count:     108
    .sgpr_spill_count: 55
    .symbol:         _Z14fwd_megakernel6Params.kd
    .uniform_work_group_size: 1
    .uses_dynamic_stack: false
    .vgpr_count:     256
    .vgpr_spill_count: 0
    .wavefront_size: 64
